# adds: static s_setprio 1 for waves 4-7 during the attention phase (reset at phase end)
# speedup vs baseline: 1.0054x; 1.0054x over previous
; #define LAS __attribute__((address_space(3)))
; __device__ __forceinline__ void attn_phase(LAS unsigned char* lds, const bf16_t* Q, const bf16_t* Kb, const bf16_t* Vt, bf16_t* AO, const float* sink, const float* qg, const float* kg) {
;     int tid = threadIdx.x; asm volatile("" : "+v"(tid));
;     const int G = gridDim.x, cidx = blockIdx.x;
;     const int wave = tid >> 6, lane = tid & 63, r = lane & 31, h = lane >> 5;
;     constexpr int KROW = 144, VROW = 776;
;     LAS unsigned char* Kl = lds; LAS unsigned char* Vl = lds + 384 * KROW;
;     float gmq = fabsf(qg[lane]), gmk = fabsf(kg[lane]);
; #pragma unroll
;     for (int o = 1; o < 64; o <<= 1) { gmq = fmaxf(gmq, __shfl_xor(gmq, o)); gmk = fmaxf(gmk, __shfl_xor(gmk, o)); }
;     const float MREF = fminf(11.5416f * 1.02f * gmq * gmk + 0.25f, 60.f);
;     u32x4 kreg[6], vreg[6];
;     ...
;     if (cidx < 1024) ATT_LOAD(cidx);
.LBB0_118:
	s_or_b64 exec, exec, s[28:29]
	v_mov_b32_e32 v8, v232
	s_waitcnt lgkmcnt(0)
	s_barrier
	v_readfirstlane_b32 s32, v232
	s_bitcmp1_b32 s32, 8
	s_cbranch_scc0 .Lattn_noprio
	s_setprio 1
.Lattn_noprio:
	v_and_b32_e32 v3, 64, v234
	v_and_b32_e32 v9, 63, v8
	v_lshlrev_b32_e32 v0, 2, v9
	global_load_dword v2, v0, s[0:1]
	s_nop 0
	global_load_dword v0, v0, s[4:5]
	v_xor_b32_e32 v4, 1, v234
	v_add_u32_e32 v3, 64, v3
	v_cmp_lt_i32_e32 vcc, v4, v3
	v_xor_b32_e32 v5, 2, v234
	v_xor_b32_e32 v6, 4, v234
	v_cndmask_b32_e32 v4, v234, v4, vcc
	v_lshlrev_b32_e32 v4, 2, v4
	v_cmp_lt_i32_e32 vcc, v5, v3
	v_xor_b32_e32 v7, 8, v234
	v_xor_b32_e32 v10, 16, v234
	v_cndmask_b32_e32 v5, v234, v5, vcc
	v_lshlrev_b32_e32 v5, 2, v5
	v_cmp_lt_i32_e32 vcc, v6, v3
	v_xor_b32_e32 v11, 32, v234
	v_readlane_b32 s2, v253, 46
	v_cndmask_b32_e32 v6, v234, v6, vcc
	v_lshlrev_b32_e32 v6, 2, v6
	v_cmp_lt_i32_e32 vcc, v7, v3
	v_readlane_b32 s3, v253, 47
	v_ashrrev_i32_e32 v199, 3, v8
	s_waitcnt vmcnt(1)
	v_and_b32_e32 v12, 0x7fffffff, v2
	s_waitcnt vmcnt(0)
	v_and_b32_e32 v13, 0x7fffffff, v0
	ds_bpermute_b32 v12, v4, v12
	ds_bpermute_b32 v4, v4, v13
	v_max_f32_e64 v2, |v2|, |v2|
	v_max_f32_e64 v0, |v0|, |v0|
	v_cndmask_b32_e64 v14, 0, 1, s[2:3]
	s_waitcnt lgkmcnt(1)
	v_max_f32_e32 v12, v12, v12
	s_waitcnt lgkmcnt(0)
	v_max_f32_e32 v4, v4, v4
	v_max_f32_e32 v2, v2, v12
	v_max_f32_e32 v0, v0, v4
	ds_bpermute_b32 v4, v5, v2
	ds_bpermute_b32 v5, v5, v0
	v_cmp_ne_u32_e64 s[0:1], 1, v14
	s_waitcnt lgkmcnt(1)
	v_max_f32_e32 v4, v4, v4
	s_waitcnt lgkmcnt(0)
	v_max_f32_e32 v5, v5, v5
	v_max_f32_e32 v2, v2, v4
	v_max_f32_e32 v0, v0, v5
	ds_bpermute_b32 v4, v6, v2
	ds_bpermute_b32 v5, v6, v0
	v_cndmask_b32_e32 v6, v234, v7, vcc
	v_lshlrev_b32_e32 v6, 2, v6
	v_cmp_lt_i32_e32 vcc, v10, v3
	s_waitcnt lgkmcnt(1)
	v_max_f32_e32 v4, v4, v4
	s_waitcnt lgkmcnt(0)
	v_max_f32_e32 v5, v5, v5
	v_max_f32_e32 v2, v2, v4
	v_max_f32_e32 v0, v0, v5
	ds_bpermute_b32 v4, v6, v2
	ds_bpermute_b32 v5, v6, v0
	v_cndmask_b32_e32 v6, v234, v10, vcc
	v_lshlrev_b32_e32 v226, 2, v6
	v_cmp_lt_i32_e32 vcc, v11, v3
	s_waitcnt lgkmcnt(1)
	v_max_f32_e32 v4, v4, v4
	s_waitcnt lgkmcnt(0)
	v_max_f32_e32 v5, v5, v5
	v_max_f32_e32 v2, v2, v4
	v_max_f32_e32 v0, v0, v5
	ds_bpermute_b32 v4, v226, v2
	ds_bpermute_b32 v5, v226, v0
	v_cndmask_b32_e32 v3, v234, v11, vcc
	v_lshlrev_b32_e32 v227, 2, v3
	s_andn2_b64 vcc, exec, s[2:3]
	s_waitcnt lgkmcnt(1)
	v_max_f32_e32 v3, v4, v4
	s_waitcnt lgkmcnt(0)
	v_max_f32_e32 v4, v5, v5
	v_max_f32_e32 v11, v2, v3
	v_max_f32_e32 v10, v0, v4
	ds_bpermute_b32 v13, v227, v11
	ds_bpermute_b32 v12, v227, v10
	v_lshlrev_b32_e32 v0, 4, v8
	v_and_b32_e32 v4, 0x70, v0
	s_cbranch_vccnz .LBB0_144
	v_readlane_b32 s2, v253, 51
	v_mov_b32_e32 v5, v1
	v_readlane_b32 s3, v253, 52
	v_mov_b32_e32 v114, v1
	v_mov_b32_e32 v115, v1
	v_lshl_add_u64 v[6:7], s[2:3], 0, v[4:5]
	v_readlane_b32 s2, v253, 49
	v_mov_b32_e32 v112, v1
	v_mov_b32_e32 v113, v1
	v_add_u32_e32 v0, s2, v199
	s_movk_i32 s2, 0x1000
	v_mov_b64_e32 v[118:119], v[114:115]
	v_cmp_gt_u32_e32 vcc, s2, v0
	v_mov_b64_e32 v[116:117], v[112:113]
	s_and_saveexec_b64 s[2:3], vcc
	s_cbranch_execz .LBB0_121
	v_readlane_b32 s4, v253, 50
	s_nop 1
	v_or_b32_e32 v2, s4, v0
	v_ashrrev_i32_e32 v3, 31, v2
	v_lshlrev_b64 v[2:3], 9, v[2:3]
	v_lshl_add_u64 v[2:3], v[6:7], 0, v[2:3]
	global_load_dwordx4 v[116:119], v[2:3], off

; __device__ __forceinline__ void attn_phase(LAS unsigned char* lds, const bf16_t* Q, const bf16_t* Kb, const bf16_t* Vt, bf16_t* AO, const float* sink, const float* qg, const float* kg) {
;     ...
;     __syncthreads();
; }
; __device__ __forceinline__ void xcd_barrier(const XcdBarrier& b) {
;     asm volatile("s_waitcnt vmcnt(0)" ::: "memory");
;     __syncthreads();
;     if (threadIdx.x == 0) {
;         unsigned* bar = b.bar;
;         __builtin_amdgcn_s_waitcnt(0);
;         unsigned nloc = b.st[0], nx = b.st[1];
;         if (nloc == 0u) { xcd_barrier_complete(bar, b.x, nloc, nx); b.st[0] = nloc; b.st[1] = nx; }
.LBB0_190:
	s_setprio 0
	s_waitcnt lgkmcnt(0)
	s_barrier
	s_waitcnt vmcnt(0)
	s_barrier
	s_and_saveexec_b64 s[0:1], s[78:79]
	s_cbranch_execz .LBB0_242
	v_readlane_b32 s2, v255, 32
	s_waitcnt vmcnt(0) expcnt(0) lgkmcnt(0)
	s_nop 0
	v_mov_b32_e32 v0, s2
	ds_read_b32 v3, v0
	v_readlane_b32 s2, v255, 33
	s_waitcnt lgkmcnt(0)
	v_cmp_ne_u32_e32 vcc, 0, v3
	v_mov_b32_e32 v0, s2
	ds_read_b32 v2, v0
	s_cbranch_vccnz .LBB0_206
	s_mov_b32 s6, 1
	s_branch .LBB0_194
